# v19: v12 + SB sign flips folded into packed adds (bit-identical math, 16 fewer VALU per tile)
# speedup vs baseline: 1.0002x; 1.0002x over previous
; #define MFMA32(a, b, c) __builtin_amdgcn_mfma_f32_32x32x16_bf16((a), (b), (c), 0, 0, 0)
; template <int MODE>
; DI bool attn_tile(const bf16x8 (&kf)[4], const bf16x8 (&vf)[4], const bf16x8 (&qf)[4], int key0, int q0, int tq, int hi, int x32, int own, unsigned selmask,
;                   float& m_run, float& l_run, f32x16& O0, f32x16& O1) {
;     f32x16 s = zero16();
; #pragma unroll
;     for (int kk = 0; kk < 4; ++kk) s = MFMA32(kf[kk], qf[kk], s);
;     if constexpr (MODE == 0) {
;         float lk[16];
;         if (key0 == q0) {
; #pragma unroll
;             for (int i = 0; i < 16; ++i) {
;                 const int key = key0 + 16 * (i >> 3) + 8 * hi + (i & 7);
;                 const bool past = key < tq;
;                 const float z = s[i] * SC2;
;                 const float l1 = __builtin_amdgcn_logf(1.f + __builtin_amdgcn_exp2f(-fabsf(z)));
;                 s[i] = past ? (fminf(z, 0.f) - l1) : -INFINITY;
;                 lk[i] = past ? -(fmaxf(z, 0.f) + l1) : 0.f;
;             }
;         } else {
; #pragma unroll
;             for (int i = 0; i < 16; ++i) {
;                 const float z = s[i] * SC2;
;                 const float l1 = __builtin_amdgcn_logf(1.f + __builtin_amdgcn_exp2f(-fabsf(z)));
;                 s[i] = fminf(z, 0.f) - l1; lk[i] = -(fmaxf(z, 0.f) + l1);
;             }
.LBB0_533:
	s_waitcnt vmcnt(0) lgkmcnt(0)
	v_mfma_f32_32x32x16_bf16 v[34:49], v[34:37], v[82:85], 0
	s_mov_b64 s[46:47], -1
	v_mfma_f32_32x32x16_bf16 v[34:49], v[54:57], v[86:89], v[34:49]
	v_mfma_f32_32x32x16_bf16 v[34:49], v[50:53], v[90:93], v[34:49]
	v_sub_co_u32_e64 v50, s[80:81], s96, 1
	s_nop 0
	v_readfirstlane_b32 s96, v50
	s_and_b64 vcc, exec, s[80:81]
	v_mfma_f32_32x32x16_bf16 v[34:49], v[58:61], v[94:97], v[34:49]
	s_cbranch_vccnz .LBB0_535
	s_nop 10
	v_mul_f32_e32 v66, 0x3e38aa3b, v39
	v_mul_f32_e32 v67, 0x3e38aa3b, v40
	v_exp_f32_e64 v65, -|v66|
	v_exp_f32_e64 v68, -|v67|
	v_mul_f32_e32 v63, 0x3e38aa3b, v38
	v_exp_f32_e64 v62, -|v63|
	v_min_f32_e32 v64, 0, v63
	v_max_f32_e32 v124, 0, v63
	v_add_f32_e32 v63, 1.0, v65
	v_min_f32_e32 v65, 0, v66
	v_max_f32_e32 v125, 0, v66
	v_add_f32_e32 v66, 1.0, v68
	v_mul_f32_e32 v68, 0x3e38aa3b, v41
	v_exp_f32_e64 v69, -|v68|
	v_min_f32_e32 v72, 0, v67
	v_max_f32_e32 v128, 0, v67
	v_mul_f32_e32 v67, 0x3e38aa3b, v42
	v_log_f32_e32 v126, v66
	v_add_f32_e32 v66, 1.0, v69
	v_exp_f32_e64 v69, -|v67|
	v_min_f32_e32 v73, 0, v68
	v_max_f32_e32 v129, 0, v68
	v_mul_f32_e32 v68, 0x3e38aa3b, v43
	v_log_f32_e32 v127, v66
	v_add_f32_e32 v66, 1.0, v69
	v_exp_f32_e64 v69, -|v68|
	v_min_f32_e32 v74, 0, v67
	v_max_f32_e32 v132, 0, v67
	v_mul_f32_e32 v67, 0x3e38aa3b, v44
	v_log_f32_e32 v130, v66
	v_add_f32_e32 v66, 1.0, v69
	v_exp_f32_e64 v69, -|v67|
	v_min_f32_e32 v75, 0, v68
	v_max_f32_e32 v133, 0, v68
	v_mul_f32_e32 v68, 0x3e38aa3b, v45
	v_log_f32_e32 v131, v66
	v_add_f32_e32 v66, 1.0, v69
	v_exp_f32_e64 v69, -|v68|
	v_min_f32_e32 v76, 0, v67
	v_max_f32_e32 v136, 0, v67
	v_mul_f32_e32 v67, 0x3e38aa3b, v46
	v_log_f32_e32 v134, v66
	v_add_f32_e32 v66, 1.0, v69
	v_exp_f32_e64 v69, -|v67|
	v_min_f32_e32 v77, 0, v68
	v_max_f32_e32 v137, 0, v68
	v_mul_f32_e32 v68, 0x3e38aa3b, v47
	v_log_f32_e32 v135, v66
	v_add_f32_e32 v66, 1.0, v69
	v_exp_f32_e64 v69, -|v68|
	v_min_f32_e32 v78, 0, v67
	v_max_f32_e32 v140, 0, v67
	v_mul_f32_e32 v67, 0x3e38aa3b, v48
	v_mul_f32_e32 v51, 0x3e38aa3b, v34
	v_mul_f32_e32 v55, 0x3e38aa3b, v35
	v_mul_f32_e32 v57, 0x3e38aa3b, v36
	v_mul_f32_e32 v61, 0x3e38aa3b, v37
	v_log_f32_e32 v138, v66
	v_add_f32_e32 v66, 1.0, v69
	v_exp_f32_e64 v69, -|v67|
	v_mul_f32_e32 v145, 0x3e38aa3b, v49
	v_exp_f32_e64 v52, -|v51|
	v_exp_f32_e64 v53, -|v55|
	v_exp_f32_e64 v56, -|v57|
	v_exp_f32_e64 v59, -|v61|
	v_min_f32_e32 v79, 0, v68
	v_max_f32_e32 v141, 0, v68
	v_exp_f32_e64 v68, -|v145|
	v_log_f32_e32 v139, v66
	v_add_f32_e32 v66, 1.0, v69
	v_min_f32_e32 v50, 0, v51
	v_add_f32_e32 v52, 1.0, v52
	v_max_f32_e32 v54, 0, v51
	v_add_f32_e32 v51, 1.0, v53
	v_add_f32_e32 v56, 1.0, v56
	v_min_f32_e32 v58, 0, v57
	v_max_f32_e32 v60, 0, v57
	v_add_f32_e32 v57, 1.0, v59
	v_add_f32_e32 v62, 1.0, v62
	v_log_f32_e32 v142, v66
	v_add_f32_e32 v66, 1.0, v68
	v_log_f32_e32 v52, v52
	v_log_f32_e32 v53, v51
	v_log_f32_e32 v56, v56
	v_log_f32_e32 v57, v57
	v_log_f32_e32 v62, v62
	v_log_f32_e32 v63, v63
	v_log_f32_e32 v143, v66
	v_min_f32_e32 v51, 0, v55
	v_max_f32_e32 v55, 0, v55
	v_min_f32_e32 v59, 0, v61
	v_max_f32_e32 v61, 0, v61
	v_max_f32_e32 v144, 0, v67
	v_min_f32_e32 v81, 0, v145
	v_max_f32_e32 v145, 0, v145
	v_min_f32_e32 v80, 0, v67
	v_pk_add_f32 v[66:67], v[50:51], v[52:53] neg_lo:[0,1] neg_hi:[0,1]
	v_pk_add_f32 v[68:69], v[58:59], v[56:57] neg_lo:[0,1] neg_hi:[0,1]
	v_pk_add_f32 v[70:71], v[64:65], v[62:63] neg_lo:[0,1] neg_hi:[0,1]
	v_pk_add_f32 v[50:51], v[54:55], v[52:53] neg_lo:[1,1] neg_hi:[1,1]
	v_pk_add_f32 v[52:53], v[60:61], v[56:57] neg_lo:[1,1] neg_hi:[1,1]
	v_pk_add_f32 v[54:55], v[124:125], v[62:63] neg_lo:[1,1] neg_hi:[1,1]
	v_pk_add_f32 v[56:57], v[128:129], v[126:127] neg_lo:[1,1] neg_hi:[1,1]
	v_pk_add_f32 v[58:59], v[132:133], v[130:131] neg_lo:[1,1] neg_hi:[1,1]
	v_pk_add_f32 v[60:61], v[136:137], v[134:135] neg_lo:[1,1] neg_hi:[1,1]
	v_pk_add_f32 v[62:63], v[140:141], v[138:139] neg_lo:[1,1] neg_hi:[1,1]
	v_pk_add_f32 v[64:65], v[144:145], v[142:143] neg_lo:[1,1] neg_hi:[1,1]
	v_pk_add_f32 v[72:73], v[72:73], v[126:127] neg_lo:[0,1] neg_hi:[0,1]
	v_pk_add_f32 v[74:75], v[74:75], v[130:131] neg_lo:[0,1] neg_hi:[0,1]
	v_pk_add_f32 v[76:77], v[76:77], v[134:135] neg_lo:[0,1] neg_hi:[0,1]
	v_pk_add_f32 v[78:79], v[78:79], v[138:139] neg_lo:[0,1] neg_hi:[0,1]
	v_pk_add_f32 v[80:81], v[80:81], v[142:143] neg_lo:[0,1] neg_hi:[0,1]
	s_mov_b64 s[46:47], 0
